# v56 variant: phase-7 out-proj weight conversion also on the 16 dedicated WGs (tail-idle WGs of phase 7 stay idle)
# baseline (speedup 1.0000x reference)
; #define LAS __attribute__((address_space(3)))
; __device__ __forceinline__ void xpose_item(const float* src, int ld, bf16_t* dst, int K, int k0, LAS float* scr, int lane, const float* gk) {
;     if (src) {
; #pragma unroll 8
;         for (int i = 0; i < 32; ++i) { const int kk = 2 * i + (lane >> 5); scr[kk * 33 + (lane & 31)] = __builtin_nontemporal_load(src + (size_t)(k0 + kk) * ld + (lane & 31)); }
;     } else {
; #pragma unroll 8
;         for (int i = 0; i < 32; ++i) { const int kk = 2 * i + (lane >> 5); scr[kk * 33 + (lane & 31)] = 0.f; }
;     }
;     const int c = lane & 7;
;     f32x4 g0 = (f32x4){1.f, 1.f, 1.f, 1.f}, g1 = g0;
;     if (gk) { g0 = *(const f32x4*)(gk + k0 + 8 * c); g1 = *(const f32x4*)(gk + k0 + 8 * c + 4); }
;     asm volatile("s_waitcnt lgkmcnt(0)" ::: "memory");
; #pragma unroll
;     for (int j = 0; j < 4; ++j) { const int n = (lane >> 3) + 8 * j; const LAS float* s = scr + (8 * c) * 33 + n;
;         u32x4 o; o.x = cvt_pk_bf16(s[0 * 33] * g0[0], s[1 * 33] * g0[1]); o.y = cvt_pk_bf16(s[2 * 33] * g0[2], s[3 * 33] * g0[3]); o.z = cvt_pk_bf16(s[4 * 33] * g1[0], s[5 * 33] * g1[1]); o.w = cvt_pk_bf16(s[6 * 33] * g1[2], s[7 * 33] * g1[3]);
;         *(u32x4*)(dst + (size_t)n * K + k0 + 8 * c) = o; }
;     asm volatile("s_waitcnt lgkmcnt(0)" ::: "memory");
; }
; __device__ __forceinline__ int xpose_all(const float* src, const float* src2, int ld, int K, int ndst, int nsrc, int mode, bf16_t* dst, int it, int NGW, LAS float* scr, int lane, const float* gvec = nullptr) {
;     const int nblk = ndst / 32, nitems = (K / 64) * nblk;
;     for (; it < nitems; it += NGW) {
;         const int kb = it / nblk, nb = it % nblk, n0 = nb * 32; const float* sp;
;         if (mode == 0) sp = (n0 < nsrc) ? src + n0 : nullptr;
;         else if (mode == 1) { const int unit = n0 >> 8, bj = (n0 >> 7) & 1, cl = n0 & 127; sp = (bj ? src2 : src) + unit * 128 + cl; }
;         else if (mode == 3) { const int pn = n0 >> 8, cl = n0 & 255; sp = src + ((pn >> 2) & 1) * 2048 + ((pn & 3) + 4 * (pn >> 3)) * 256 + cl; }
;         else { const int unit = n0 >> 8, bj = (n0 >> 7) & 1, cl = n0 & 127; sp = (bj ? src2 : src) + (size_t)(unit >> 1) * 65536 + (unit & 1) * 128 + cl; }
;         xpose_item(sp, ld, dst + (size_t)n0 * K, K, kb * 64, scr, lane, gvec);
.Lxpwid7_end:
	s_sub_i32 s59, s59, 0x2840
	s_cmpk_ge_i32 s59, 0x1000
	s_cbranch_scc1 .Lxpwod7_end
	s_load_dwordx2 s[60:61], s[92:93], 0xb0
	s_load_dwordx2 s[62:63], s[92:93], 0xe8
	v_mov_b32_e32 v5, 0x2000
	v_mul_u32_u24_e32 v5, v3, v5
	v_add_u32_e32 v5, v5, v4
	v_mov_b32_e32 v10, 0x2000
	v_mul_u32_u24_e32 v10, v8, v10
	v_lshl_add_u32 v12, v7, 4, v10
	v_add_u32_e32 v13, 0x10000, v12
	v_add_u32_e32 v14, 0x20000, v12
	v_add_u32_e32 v15, 0x30000, v12
	s_waitcnt lgkmcnt(0)
	s_add_u32 s62, s62, 0xad00000
	s_addc_u32 s63, s63, 0
	s_lshr_b32 s64, s59, 6
	s_and_b32 s65, s59, 63
	s_mul_i32 s66, s64, 0x80000
	s_lshl_b32 s67, s65, 7
	s_add_i32 s66, s66, s67
	s_add_u32 s66, s60, s66
	s_addc_u32 s67, s61, 0
	v_mov_b32_e32 v11, v5
	global_load_dword v20, v11, s[66:67] nt
	v_add_u32_e32 v11, 0x4000, v11
	global_load_dword v21, v11, s[66:67] nt
	v_add_u32_e32 v11, 0x4000, v11
	global_load_dword v22, v11, s[66:67] nt
	v_add_u32_e32 v11, 0x4000, v11
	global_load_dword v23, v11, s[66:67] nt
	v_add_u32_e32 v11, 0x4000, v11
	global_load_dword v24, v11, s[66:67] nt
	v_add_u32_e32 v11, 0x4000, v11
	global_load_dword v25, v11, s[66:67] nt
	v_add_u32_e32 v11, 0x4000, v11
	global_load_dword v26, v11, s[66:67] nt
	v_add_u32_e32 v11, 0x4000, v11
	global_load_dword v27, v11, s[66:67] nt
	v_add_u32_e32 v11, 0x4000, v11
	global_load_dword v28, v11, s[66:67] nt
	v_add_u32_e32 v11, 0x4000, v11
	global_load_dword v29, v11, s[66:67] nt
	v_add_u32_e32 v11, 0x4000, v11
	global_load_dword v30, v11, s[66:67] nt
	v_add_u32_e32 v11, 0x4000, v11
	global_load_dword v31, v11, s[66:67] nt
	v_add_u32_e32 v11, 0x4000, v11
	global_load_dword v32, v11, s[66:67] nt
	v_add_u32_e32 v11, 0x4000, v11
	global_load_dword v33, v11, s[66:67] nt
	v_add_u32_e32 v11, 0x4000, v11
	global_load_dword v34, v11, s[66:67] nt
	v_add_u32_e32 v11, 0x4000, v11
	global_load_dword v35, v11, s[66:67] nt
	v_add_u32_e32 v11, 0x4000, v11
	global_load_dword v36, v11, s[66:67] nt
	v_add_u32_e32 v11, 0x4000, v11
	global_load_dword v37, v11, s[66:67] nt
	v_add_u32_e32 v11, 0x4000, v11
	global_load_dword v38, v11, s[66:67] nt
	v_add_u32_e32 v11, 0x4000, v11
	global_load_dword v39, v11, s[66:67] nt
	v_add_u32_e32 v11, 0x4000, v11
	global_load_dword v40, v11, s[66:67] nt
	v_add_u32_e32 v11, 0x4000, v11
	global_load_dword v41, v11, s[66:67] nt
	v_add_u32_e32 v11, 0x4000, v11
	global_load_dword v42, v11, s[66:67] nt
	v_add_u32_e32 v11, 0x4000, v11
	global_load_dword v43, v11, s[66:67] nt
	v_add_u32_e32 v11, 0x4000, v11
	global_load_dword v44, v11, s[66:67] nt
	v_add_u32_e32 v11, 0x4000, v11
	global_load_dword v45, v11, s[66:67] nt
	v_add_u32_e32 v11, 0x4000, v11
	global_load_dword v46, v11, s[66:67] nt
	v_add_u32_e32 v11, 0x4000, v11
	global_load_dword v47, v11, s[66:67] nt
	v_add_u32_e32 v11, 0x4000, v11
	global_load_dword v48, v11, s[66:67] nt
	v_add_u32_e32 v11, 0x4000, v11
	global_load_dword v49, v11, s[66:67] nt
	v_add_u32_e32 v11, 0x4000, v11
	global_load_dword v50, v11, s[66:67] nt
	v_add_u32_e32 v11, 0x4000, v11
	global_load_dword v51, v11, s[66:67] nt
.Lxpwod7_loop:
	s_add_i32 s32, s59, 0x80
	s_cmpk_lt_i32 s32, 0x1000
	s_cbranch_scc0 .Lxpwod7_dumB
	s_lshr_b32 s64, s32, 6
	s_and_b32 s65, s32, 63
	s_mul_i32 s66, s64, 0x80000
	s_lshl_b32 s67, s65, 7
	s_add_i32 s66, s66, s67
	s_add_u32 s66, s60, s66
	s_addc_u32 s67, s61, 0
	v_mov_b32_e32 v11, v5
	global_load_dword v108, v11, s[66:67] nt
	v_add_u32_e32 v11, 0x4000, v11
	global_load_dword v109, v11, s[66:67] nt
	v_add_u32_e32 v11, 0x4000, v11
	global_load_dword v110, v11, s[66:67] nt
	v_add_u32_e32 v11, 0x4000, v11
	global_load_dword v111, v11, s[66:67] nt
	v_add_u32_e32 v11, 0x4000, v11
	global_load_dword v112, v11, s[66:67] nt
	v_add_u32_e32 v11, 0x4000, v11
	global_load_dword v113, v11, s[66:67] nt
	v_add_u32_e32 v11, 0x4000, v11
	global_load_dword v114, v11, s[66:67] nt
	v_add_u32_e32 v11, 0x4000, v11
	global_load_dword v115, v11, s[66:67] nt
	v_add_u32_e32 v11, 0x4000, v11
	global_load_dword v116, v11, s[66:67] nt
	v_add_u32_e32 v11, 0x4000, v11
	global_load_dword v117, v11, s[66:67] nt
	v_add_u32_e32 v11, 0x4000, v11
	global_load_dword v118, v11, s[66:67] nt
	v_add_u32_e32 v11, 0x4000, v11
	global_load_dword v119, v11, s[66:67] nt
	v_add_u32_e32 v11, 0x4000, v11
	global_load_dword v120, v11, s[66:67] nt
	v_add_u32_e32 v11, 0x4000, v11
	global_load_dword v121, v11, s[66:67] nt
	v_add_u32_e32 v11, 0x4000, v11
	global_load_dword v122, v11, s[66:67] nt
	v_add_u32_e32 v11, 0x4000, v11
	global_load_dword v123, v11, s[66:67] nt
	v_add_u32_e32 v11, 0x4000, v11
	global_load_dword v124, v11, s[66:67] nt
	v_add_u32_e32 v11, 0x4000, v11
	global_load_dword v125, v11, s[66:67] nt
	v_add_u32_e32 v11, 0x4000, v11
	global_load_dword v126, v11, s[66:67] nt
	v_add_u32_e32 v11, 0x4000, v11
	global_load_dword v127, v11, s[66:67] nt
	v_add_u32_e32 v11, 0x4000, v11
	global_load_dword v128, v11, s[66:67] nt
	v_add_u32_e32 v11, 0x4000, v11
	global_load_dword v129, v11, s[66:67] nt
	v_add_u32_e32 v11, 0x4000, v11
	global_load_dword v130, v11, s[66:67] nt
	v_add_u32_e32 v11, 0x4000, v11
	global_load_dword v131, v11, s[66:67] nt
	v_add_u32_e32 v11, 0x4000, v11
	global_load_dword v132, v11, s[66:67] nt
	v_add_u32_e32 v11, 0x4000, v11
	global_load_dword v133, v11, s[66:67] nt
	v_add_u32_e32 v11, 0x4000, v11
	global_load_dword v134, v11, s[66:67] nt
	v_add_u32_e32 v11, 0x4000, v11
	global_load_dword v135, v11, s[66:67] nt
	v_add_u32_e32 v11, 0x4000, v11
	global_load_dword v136, v11, s[66:67] nt
	v_add_u32_e32 v11, 0x4000, v11
	global_load_dword v137, v11, s[66:67] nt
	v_add_u32_e32 v11, 0x4000, v11
	global_load_dword v138, v11, s[66:67] nt
	v_add_u32_e32 v11, 0x4000, v11
	global_load_dword v139, v11, s[66:67] nt
	s_branch .Lxpwod7_procA

; #define LAS __attribute__((address_space(3)))
; __device__ __forceinline__ unsigned cvt_pk_bf16(float lo, float hi) { unsigned r; asm volatile("v_cvt_pk_bf16_f32 %0, %1, %2" : "=v"(r) : "v"(lo), "v"(hi)); return r; }
; __device__ __forceinline__ void xpose_item(const float* src, int ld, bf16_t* dst, int K, int k0, LAS float* scr, int lane, const float* gk) {
;     ...
;         for (int i = 0; i < 32; ++i) { const int kk = 2 * i + (lane >> 5); scr[kk * 33 + (lane & 31)] = __builtin_nontemporal_load(src + (size_t)(k0 + kk) * ld + (lane & 31)); }
;     } else {
; #pragma unroll 8
;         for (int i = 0; i < 32; ++i) { const int kk = 2 * i + (lane >> 5); scr[kk * 33 + (lane & 31)] = 0.f; }
;     }
;     const int c = lane & 7;
;     f32x4 g0 = (f32x4){1.f, 1.f, 1.f, 1.f}, g1 = g0;
;     if (gk) { g0 = *(const f32x4*)(gk + k0 + 8 * c); g1 = *(const f32x4*)(gk + k0 + 8 * c + 4); }
;     asm volatile("s_waitcnt lgkmcnt(0)" ::: "memory");
; #pragma unroll
;     for (int j = 0; j < 4; ++j) { const int n = (lane >> 3) + 8 * j; const LAS float* s = scr + (8 * c) * 33 + n;
;         u32x4 o; o.x = cvt_pk_bf16(s[0 * 33] * g0[0], s[1 * 33] * g0[1]); o.y = cvt_pk_bf16(s[2 * 33] * g0[2], s[3 * 33] * g0[3]); o.z = cvt_pk_bf16(s[4 * 33] * g1[0], s[5 * 33] * g1[1]); o.w = cvt_pk_bf16(s[6 * 33] * g1[2], s[7 * 33] * g1[3]);
;         *(u32x4*)(dst + (size_t)n * K + k0 + 8 * c) = o; }
.Lxpwod7_procA:
	s_lshr_b32 s64, s59, 6
	s_and_b32 s65, s59, 63
	s_mul_i32 s68, s65, 0x40000
	s_lshl_b32 s64, s64, 7
	s_add_i32 s68, s68, s64
	s_add_u32 s64, s62, s68
	s_addc_u32 s65, s63, 0
	s_waitcnt vmcnt(63)
	ds_write_b32 v6, v20 offset:0
	s_waitcnt vmcnt(62)
	ds_write_b32 v6, v21 offset:264
	s_waitcnt vmcnt(61)
	ds_write_b32 v6, v22 offset:528
	s_waitcnt vmcnt(60)
	ds_write_b32 v6, v23 offset:792
	s_waitcnt vmcnt(59)
	ds_write_b32 v6, v24 offset:1056
	s_waitcnt vmcnt(58)
	ds_write_b32 v6, v25 offset:1320
	s_waitcnt vmcnt(57)
	ds_write_b32 v6, v26 offset:1584
	s_waitcnt vmcnt(56)
	ds_write_b32 v6, v27 offset:1848
	s_waitcnt vmcnt(55)
	ds_write_b32 v6, v28 offset:2112
	s_waitcnt vmcnt(54)
	ds_write_b32 v6, v29 offset:2376
	s_waitcnt vmcnt(53)
	ds_write_b32 v6, v30 offset:2640
	s_waitcnt vmcnt(52)
	ds_write_b32 v6, v31 offset:2904
	s_waitcnt vmcnt(51)
	ds_write_b32 v6, v32 offset:3168
	s_waitcnt vmcnt(50)
	ds_write_b32 v6, v33 offset:3432
	s_waitcnt vmcnt(49)
	ds_write_b32 v6, v34 offset:3696
	s_waitcnt vmcnt(48)
	ds_write_b32 v6, v35 offset:3960
	s_waitcnt vmcnt(47)
	ds_write_b32 v6, v36 offset:4224
	s_waitcnt vmcnt(46)
	ds_write_b32 v6, v37 offset:4488
	s_waitcnt vmcnt(45)
	ds_write_b32 v6, v38 offset:4752
	s_waitcnt vmcnt(44)
	ds_write_b32 v6, v39 offset:5016
	s_waitcnt vmcnt(43)
	ds_write_b32 v6, v40 offset:5280
	s_waitcnt vmcnt(42)
	ds_write_b32 v6, v41 offset:5544
	s_waitcnt vmcnt(41)
	ds_write_b32 v6, v42 offset:5808
	s_waitcnt vmcnt(40)
	ds_write_b32 v6, v43 offset:6072
	s_waitcnt vmcnt(39)
	ds_write_b32 v6, v44 offset:6336
	s_waitcnt vmcnt(38)
	ds_write_b32 v6, v45 offset:6600
	s_waitcnt vmcnt(37)
	ds_write_b32 v6, v46 offset:6864
	s_waitcnt vmcnt(36)
	ds_write_b32 v6, v47 offset:7128
	s_waitcnt vmcnt(35)
	ds_write_b32 v6, v48 offset:7392
	s_waitcnt vmcnt(34)
	ds_write_b32 v6, v49 offset:7656
	s_waitcnt vmcnt(33)
	ds_write_b32 v6, v50 offset:7920
	s_waitcnt vmcnt(32)
	ds_write_b32 v6, v51 offset:8184
	s_waitcnt lgkmcnt(0)
	ds_read2_b32 v[60:61], v9 offset0:0 offset1:33
	ds_read2_b32 v[62:63], v9 offset0:66 offset1:99
	ds_read2_b32 v[64:65], v9 offset0:132 offset1:165
	ds_read2_b32 v[66:67], v9 offset0:198 offset1:231
	ds_read2_b32 v[68:69], v9 offset0:8 offset1:41
	ds_read2_b32 v[70:71], v9 offset0:74 offset1:107
	ds_read2_b32 v[72:73], v9 offset0:140 offset1:173
	ds_read2_b32 v[74:75], v9 offset0:206 offset1:239
	ds_read2_b32 v[76:77], v9 offset0:16 offset1:49
	ds_read2_b32 v[78:79], v9 offset0:82 offset1:115
	ds_read2_b32 v[80:81], v9 offset0:148 offset1:181
	ds_read2_b32 v[82:83], v9 offset0:214 offset1:247
	ds_read2_b32 v[84:85], v9 offset0:24 offset1:57
	ds_read2_b32 v[86:87], v9 offset0:90 offset1:123
	ds_read2_b32 v[88:89], v9 offset0:156 offset1:189
	ds_read2_b32 v[90:91], v9 offset0:222 offset1:255
	s_waitcnt lgkmcnt(12)
	v_cvt_pk_bf16_f32 v92, v60, v61
	v_cvt_pk_bf16_f32 v93, v62, v63
	v_cvt_pk_bf16_f32 v94, v64, v65
	v_cvt_pk_bf16_f32 v95, v66, v67
	global_store_dwordx4 v12, v[92:95], s[64:65]
	s_waitcnt lgkmcnt(8)
	v_cvt_pk_bf16_f32 v96, v68, v69
	v_cvt_pk_bf16_f32 v97, v70, v71
	v_cvt_pk_bf16_f32 v98, v72, v73
	v_cvt_pk_bf16_f32 v99, v74, v75
	global_store_dwordx4 v13, v[96:99], s[64:65]
	s_waitcnt lgkmcnt(4)
	v_cvt_pk_bf16_f32 v100, v76, v77
	v_cvt_pk_bf16_f32 v101, v78, v79
	v_cvt_pk_bf16_f32 v102, v80, v81
	v_cvt_pk_bf16_f32 v103, v82, v83
	global_store_dwordx4 v14, v[100:103], s[64:65]
	s_waitcnt lgkmcnt(0)
	v_cvt_pk_bf16_f32 v104, v84, v85
	v_cvt_pk_bf16_f32 v105, v86, v87
	v_cvt_pk_bf16_f32 v106, v88, v89
	v_cvt_pk_bf16_f32 v107, v90, v91
	global_store_dwordx4 v15, v[104:107], s[64:65]
	s_cmpk_lt_i32 s32, 0x1000
	s_cbranch_scc0 .Lxpwod7_fin
	s_add_i32 s59, s32, 0x80
	s_cmpk_lt_i32 s59, 0x1000
	s_cbranch_scc0 .Lxpwod7_dumA
	s_lshr_b32 s64, s59, 6
	s_and_b32 s65, s59, 63
	s_mul_i32 s66, s64, 0x80000
	s_lshl_b32 s67, s65, 7
	s_add_i32 s66, s66, s67
	s_add_u32 s66, s60, s66
	s_addc_u32 s67, s61, 0
	v_mov_b32_e32 v11, v5
	global_load_dword v20, v11, s[66:67] nt
	v_add_u32_e32 v11, 0x4000, v11
	global_load_dword v21, v11, s[66:67] nt
	v_add_u32_e32 v11, 0x4000, v11
	global_load_dword v22, v11, s[66:67] nt
	v_add_u32_e32 v11, 0x4000, v11
	global_load_dword v23, v11, s[66:67] nt
	v_add_u32_e32 v11, 0x4000, v11
	global_load_dword v24, v11, s[66:67] nt
	v_add_u32_e32 v11, 0x4000, v11
	global_load_dword v25, v11, s[66:67] nt
	v_add_u32_e32 v11, 0x4000, v11
	global_load_dword v26, v11, s[66:67] nt
	v_add_u32_e32 v11, 0x4000, v11
	global_load_dword v27, v11, s[66:67] nt
	v_add_u32_e32 v11, 0x4000, v11
	global_load_dword v28, v11, s[66:67] nt
	v_add_u32_e32 v11, 0x4000, v11
	global_load_dword v29, v11, s[66:67] nt
	v_add_u32_e32 v11, 0x4000, v11
	global_load_dword v30, v11, s[66:67] nt
	v_add_u32_e32 v11, 0x4000, v11
	global_load_dword v31, v11, s[66:67] nt
	v_add_u32_e32 v11, 0x4000, v11
	global_load_dword v32, v11, s[66:67] nt
	v_add_u32_e32 v11, 0x4000, v11
	global_load_dword v33, v11, s[66:67] nt
	v_add_u32_e32 v11, 0x4000, v11
	global_load_dword v34, v11, s[66:67] nt
	v_add_u32_e32 v11, 0x4000, v11
	global_load_dword v35, v11, s[66:67] nt
	v_add_u32_e32 v11, 0x4000, v11
	global_load_dword v36, v11, s[66:67] nt
	v_add_u32_e32 v11, 0x4000, v11
	global_load_dword v37, v11, s[66:67] nt
	v_add_u32_e32 v11, 0x4000, v11
	global_load_dword v38, v11, s[66:67] nt
	v_add_u32_e32 v11, 0x4000, v11
	global_load_dword v39, v11, s[66:67] nt
	v_add_u32_e32 v11, 0x4000, v11
	global_load_dword v40, v11, s[66:67] nt
	v_add_u32_e32 v11, 0x4000, v11
	global_load_dword v41, v11, s[66:67] nt
	v_add_u32_e32 v11, 0x4000, v11
	global_load_dword v42, v11, s[66:67] nt
	v_add_u32_e32 v11, 0x4000, v11
	global_load_dword v43, v11, s[66:67] nt
	v_add_u32_e32 v11, 0x4000, v11
	global_load_dword v44, v11, s[66:67] nt
	v_add_u32_e32 v11, 0x4000, v11
	global_load_dword v45, v11, s[66:67] nt
	v_add_u32_e32 v11, 0x4000, v11
	global_load_dword v46, v11, s[66:67] nt
	v_add_u32_e32 v11, 0x4000, v11
	global_load_dword v47, v11, s[66:67] nt
	v_add_u32_e32 v11, 0x4000, v11
	global_load_dword v48, v11, s[66:67] nt
	v_add_u32_e32 v11, 0x4000, v11
	global_load_dword v49, v11, s[66:67] nt
	v_add_u32_e32 v11, 0x4000, v11
	global_load_dword v50, v11, s[66:67] nt
	v_add_u32_e32 v11, 0x4000, v11
	global_load_dword v51, v11, s[66:67] nt
	s_branch .Lxpwod7_procB
